# nsa-sel-direct-table-bias
# baseline (speedup 1.0000x reference)
; #define LAS __attribute__((address_space(3)))
; __device__ __forceinline__ v16f mfma32(v8s a, v8s b, v16f c) { return __builtin_amdgcn_mfma_f32_32x32x16_bf16(a, b, c, 0, 0, 0); }
; __device__ __forceinline__ void pv_mma(const v4s (&vf)[16], const v16f& p0, const v16f& p1, v16f (&oT)[2]) {
;     v4u w[4];
;     w[0] = (v4u){pkbf(p0[0], p0[1]), pkbf(p0[2], p0[3]), pkbf(p0[4], p0[5]), pkbf(p0[6], p0[7])};
;     w[1] = (v4u){pkbf(p0[8], p0[9]), pkbf(p0[10], p0[11]), pkbf(p0[12], p0[13]), pkbf(p0[14], p0[15])};
;     w[2] = (v4u){pkbf(p1[0], p1[1]), pkbf(p1[2], p1[3]), pkbf(p1[4], p1[5]), pkbf(p1[6], p1[7])};
;     w[3] = (v4u){pkbf(p1[8], p1[9]), pkbf(p1[10], p1[11]), pkbf(p1[12], p1[13]), pkbf(p1[14], p1[15])};
; #pragma unroll
;     for (int ks = 0; ks < 4; ++ks)
; #pragma unroll
;         for (int dt = 0; dt < 2; ++dt) {
;             const v4s lo = vf[4 * ks + 2 * dt], h4 = vf[4 * ks + 2 * dt + 1];
;             const v8s af = (v8s){lo[0], lo[1], lo[2], lo[3], h4[0], h4[1], h4[2], h4[3]};
;             oT[dt] = mfma32(af, __builtin_bit_cast(v8s, w[ks]), oT[dt]);
;         }
;     __device__ __forceinline__ void apply_tab(v16f& p0, v16f& p1, int t) const {
;         const LAS float* bp = tb + (NEGPAD + qpos - 64 * t - 63 - 4 * hi);
;         v16f c0, c1;
; #pragma unroll
;         for (int r = 0; r < 16; ++r) { c0[r] = bp[63 - ((r & 3) + 8 * (r >> 2))]; c1[r] = bp[31 - ((r & 3) + 8 * (r >> 2))]; }
;         p0 = p0 * C1 + c0; p1 = p1 * C1 + c1;
;     }
.LBB0_537:
	v_cmp_neq_f32_e32 vcc, s76, v217
	s_nop 1
	v_cndmask_b32_e32 v0, 0, v217, vcc
	v_cndmask_b32_e64 v6, v0, v240, s[0:1]
	v_sub_f32_e32 v2, v73, v6
	v_sub_f32_e32 v3, v72, v6
	v_sub_f32_e32 v4, v71, v6
	v_sub_f32_e32 v5, v70, v6
	v_sub_f32_e32 v15, v69, v6
	v_sub_f32_e32 v16, v68, v6
	v_sub_f32_e32 v17, v67, v6
	v_sub_f32_e32 v18, v66, v6
	v_exp_f32_e32 v66, v18
	v_exp_f32_e32 v67, v17
	v_exp_f32_e32 v68, v16
	v_exp_f32_e32 v69, v15
	v_exp_f32_e32 v70, v5
	v_exp_f32_e32 v71, v4
	v_exp_f32_e32 v72, v3
	v_exp_f32_e32 v73, v2
	v_cvt_pk_bf16_f32 v2, v66, v67
	v_cvt_pk_bf16_f32 v3, v68, v69
	v_cvt_pk_bf16_f32 v4, v70, v71
	v_cvt_pk_bf16_f32 v5, v72, v73
	v_sub_f32_e32 v7, v81, v6
	v_sub_f32_e32 v8, v80, v6
	s_waitcnt lgkmcnt(2)
	v_mfma_f32_32x32x16_bf16 v[34:49], v[182:185], v[2:5], v[34:49]
	v_sub_f32_e32 v9, v79, v6
	v_sub_f32_e32 v10, v78, v6
	v_sub_f32_e32 v11, v77, v6
	v_sub_f32_e32 v12, v76, v6
	v_sub_f32_e32 v13, v75, v6
	v_sub_f32_e32 v14, v74, v6
	v_exp_f32_e32 v74, v14
	v_mfma_f32_32x32x16_bf16 v[50:65], v[178:181], v[2:5], v[50:65]
	v_exp_f32_e32 v75, v13
	v_exp_f32_e32 v76, v12
	v_exp_f32_e32 v77, v11
	v_exp_f32_e32 v78, v10
	v_exp_f32_e32 v79, v9
	v_exp_f32_e32 v80, v8
	v_exp_f32_e32 v81, v7
	v_cvt_pk_bf16_f32 v2, v74, v75
	v_cvt_pk_bf16_f32 v3, v76, v77
	v_cvt_pk_bf16_f32 v4, v78, v79
	v_cvt_pk_bf16_f32 v5, v80, v81
	v_sub_f32_e32 v26, v89, v6
	v_sub_f32_e32 v27, v88, v6
	v_mfma_f32_32x32x16_bf16 v[34:49], v[174:177], v[2:5], v[34:49]
	v_sub_f32_e32 v28, v87, v6
	v_sub_f32_e32 v29, v86, v6
	v_sub_f32_e32 v15, v85, v6
	v_sub_f32_e32 v16, v84, v6
	v_sub_f32_e32 v7, v83, v6
	v_sub_f32_e32 v8, v82, v6
	v_exp_f32_e32 v82, v8
	v_mfma_f32_32x32x16_bf16 v[50:65], v[170:173], v[2:5], v[50:65]
	v_exp_f32_e32 v83, v7
	v_exp_f32_e32 v84, v16
	v_exp_f32_e32 v85, v15
	v_exp_f32_e32 v86, v29
	v_exp_f32_e32 v87, v28
	v_exp_f32_e32 v88, v27
	v_exp_f32_e32 v89, v26
	v_cvt_pk_bf16_f32 v2, v82, v83
	v_cvt_pk_bf16_f32 v3, v84, v85
	v_cvt_pk_bf16_f32 v4, v86, v87
	v_cvt_pk_bf16_f32 v5, v88, v89
	v_sub_f32_e32 v19, v97, v6
	v_sub_f32_e32 v20, v96, v6
	v_mfma_f32_32x32x16_bf16 v[34:49], v[166:169], v[2:5], v[34:49]
	v_sub_f32_e32 v21, v95, v6
	v_sub_f32_e32 v22, v94, v6
	v_sub_f32_e32 v23, v93, v6
	v_sub_f32_e32 v24, v92, v6
	v_sub_f32_e32 v25, v91, v6
	v_sub_f32_e32 v6, v90, v6
	v_exp_f32_e32 v90, v6
	v_mfma_f32_32x32x16_bf16 v[50:65], v[162:165], v[2:5], v[50:65]
	v_exp_f32_e32 v91, v25
	v_exp_f32_e32 v92, v24
	v_exp_f32_e32 v93, v23
	v_exp_f32_e32 v94, v22
	v_exp_f32_e32 v95, v21
	v_exp_f32_e32 v96, v20
	v_exp_f32_e32 v97, v19
	s_nop 3
	v_cvt_pk_bf16_f32 v162, v90, v91
	v_cvt_pk_bf16_f32 v163, v92, v93
	v_cvt_pk_bf16_f32 v164, v94, v95
	v_cvt_pk_bf16_f32 v165, v96, v97
	s_nop 1
	v_mfma_f32_32x32x16_bf16 v[34:49], v[158:161], v[162:165], v[34:49]
	s_andn2_b64 vcc, exec, s[24:25]
	s_waitcnt lgkmcnt(0)
	v_mfma_f32_32x32x16_bf16 v[50:65], v[154:157], v[162:165], v[50:65]
	s_cbranch_vccnz .LBB0_543
	s_lshl_b32 s24, s50, 6
	s_sub_i32 s0, s49, s24
	s_cmpk_lt_i32 s0, 0x400
	s_mov_b64 s[0:1], -1
	s_cbranch_scc0 .LBB0_540
	v_add_u32_e32 v2, s24, v200
	v_sub_u32_e32 v2, v199, v2
	v_lshl_add_u32 v18, v2, 2, s37
	v_add_u32_e32 v18, 0xd110, v18
	ds_read2_b32 v[2:3], v18 offset0:58 offset1:59
	ds_read2_b32 v[154:155], v18 offset0:26 offset1:27
	ds_read2_b32 v[4:5], v18 offset0:56 offset1:57
	ds_read2_b32 v[20:21], v18 offset0:24 offset1:25
	ds_read2_b32 v[6:7], v18 offset0:50 offset1:51
	ds_read2_b32 v[22:23], v18 offset0:18 offset1:19
	ds_read2_b32 v[8:9], v18 offset0:48 offset1:49
	ds_read2_b32 v[24:25], v18 offset0:16 offset1:17
	ds_read2_b32 v[10:11], v18 offset0:42 offset1:43
	ds_read2_b32 v[26:27], v18 offset0:10 offset1:11
	ds_read2_b32 v[12:13], v18 offset0:40 offset1:41
	ds_read2_b32 v[28:29], v18 offset0:8 offset1:9
	ds_read2_b32 v[14:15], v18 offset0:34 offset1:35
	ds_read2_b32 v[16:17], v18 offset0:32 offset1:33
	ds_read2_b32 v[30:31], v18 offset0:0 offset1:1
	ds_read2_b32 v[32:33], v18 offset0:2 offset1:3
	s_waitcnt lgkmcnt(0)
	v_pk_fma_f32 v[124:125], v[124:125], s[52:53], v[12:13] op_sel:[0,0,1] op_sel_hi:[1,0,0]
	v_pk_fma_f32 v[122:123], v[122:123], s[52:53], v[10:11] op_sel:[0,0,1] op_sel_hi:[1,0,0]
	v_pk_fma_f32 v[126:127], v[126:127], s[52:53], v[14:15] op_sel:[0,0,1] op_sel_hi:[1,0,0]
	v_pk_fma_f32 v[128:129], v[128:129], s[52:53], v[16:17] op_sel:[0,0,1] op_sel_hi:[1,0,0]
	v_pk_fma_f32 v[120:121], v[120:121], s[52:53], v[8:9] op_sel:[0,0,1] op_sel_hi:[1,0,0]
	v_pk_fma_f32 v[118:119], v[118:119], s[52:53], v[6:7] op_sel:[0,0,1] op_sel_hi:[1,0,0]
	v_pk_fma_f32 v[116:117], v[116:117], s[52:53], v[4:5] op_sel:[0,0,1] op_sel_hi:[1,0,0]
	v_pk_fma_f32 v[114:115], v[114:115], s[52:53], v[2:3] op_sel:[0,0,1] op_sel_hi:[1,0,0]
	v_pk_fma_f32 v[112:113], v[112:113], s[52:53], v[30:31] op_sel:[0,0,1] op_sel_hi:[1,0,0]
	v_pk_fma_f32 v[110:111], v[110:111], s[52:53], v[32:33] op_sel:[0,0,1] op_sel_hi:[1,0,0]
	v_pk_fma_f32 v[108:109], v[108:109], s[52:53], v[28:29] op_sel:[0,0,1] op_sel_hi:[1,0,0]
	v_pk_fma_f32 v[106:107], v[106:107], s[52:53], v[26:27] op_sel:[0,0,1] op_sel_hi:[1,0,0]
	v_pk_fma_f32 v[104:105], v[104:105], s[52:53], v[24:25] op_sel:[0,0,1] op_sel_hi:[1,0,0]
	v_pk_fma_f32 v[102:103], v[102:103], s[52:53], v[22:23] op_sel:[0,0,1] op_sel_hi:[1,0,0]
	v_pk_fma_f32 v[100:101], v[100:101], s[52:53], v[20:21] op_sel:[0,0,1] op_sel_hi:[1,0,0]
	v_pk_fma_f32 v[98:99], v[98:99], s[52:53], v[154:155] op_sel:[0,0,1] op_sel_hi:[1,0,0]
	s_mov_b64 s[0:1], 0
	s_branch .LBB0_543

; #define LAS __attribute__((address_space(3)))
; __device__ __forceinline__ v16f mfma32(v8s a, v8s b, v16f c) { return __builtin_amdgcn_mfma_f32_32x32x16_bf16(a, b, c, 0, 0, 0); }
; __device__ __forceinline__ void pv_mma(const v4s (&vf)[16], const v16f& p0, const v16f& p1, v16f (&oT)[2]) {
;     v4u w[4];
;     w[0] = (v4u){pkbf(p0[0], p0[1]), pkbf(p0[2], p0[3]), pkbf(p0[4], p0[5]), pkbf(p0[6], p0[7])};
;     w[1] = (v4u){pkbf(p0[8], p0[9]), pkbf(p0[10], p0[11]), pkbf(p0[12], p0[13]), pkbf(p0[14], p0[15])};
;     w[2] = (v4u){pkbf(p1[0], p1[1]), pkbf(p1[2], p1[3]), pkbf(p1[4], p1[5]), pkbf(p1[6], p1[7])};
;     w[3] = (v4u){pkbf(p1[8], p1[9]), pkbf(p1[10], p1[11]), pkbf(p1[12], p1[13]), pkbf(p1[14], p1[15])};
; #pragma unroll
;     for (int ks = 0; ks < 4; ++ks)
; #pragma unroll
;         for (int dt = 0; dt < 2; ++dt) {
;             const v4s lo = vf[4 * ks + 2 * dt], h4 = vf[4 * ks + 2 * dt + 1];
;             const v8s af = (v8s){lo[0], lo[1], lo[2], lo[3], h4[0], h4[1], h4[2], h4[3]};
;             oT[dt] = mfma32(af, __builtin_bit_cast(v8s, w[ks]), oT[dt]);
;         }
;     __device__ __forceinline__ void apply_tab(v16f& p0, v16f& p1, int t) const {
;         const LAS float* bp = tb + (NEGPAD + qpos - 64 * t - 63 - 4 * hi);
;         v16f c0, c1;
; #pragma unroll
;         for (int r = 0; r < 16; ++r) { c0[r] = bp[63 - ((r & 3) + 8 * (r >> 2))]; c1[r] = bp[31 - ((r & 3) + 8 * (r >> 2))]; }
;         p0 = p0 * C1 + c0; p1 = p1 * C1 + c1;
;     }
.LBB0_552:
	v_cndmask_b32_e64 v0, v0, v240, s[4:5]
	v_sub_f32_e32 v121, v121, v0
	v_sub_f32_e32 v120, v120, v0
	v_sub_f32_e32 v119, v119, v0
	v_sub_f32_e32 v118, v118, v0
	v_sub_f32_e32 v117, v117, v0
	v_sub_f32_e32 v116, v116, v0
	v_sub_f32_e32 v115, v115, v0
	v_sub_f32_e32 v114, v114, v0
	v_exp_f32_e32 v114, v114
	v_exp_f32_e32 v115, v115
	v_exp_f32_e32 v116, v116
	v_exp_f32_e32 v117, v117
	v_exp_f32_e32 v118, v118
	v_exp_f32_e32 v119, v119
	v_exp_f32_e32 v120, v120
	v_exp_f32_e32 v121, v121
	v_sub_f32_e32 v154, v105, v0
	v_sub_f32_e32 v155, v104, v0
	v_sub_f32_e32 v156, v103, v0
	v_sub_f32_e32 v157, v102, v0
	v_cvt_pk_bf16_f32 v102, v114, v115
	v_cvt_pk_bf16_f32 v103, v116, v117
	v_cvt_pk_bf16_f32 v104, v118, v119
	v_cvt_pk_bf16_f32 v105, v120, v121
	v_sub_f32_e32 v129, v129, v0
	v_sub_f32_e32 v128, v128, v0
	s_waitcnt lgkmcnt(2)
	v_mfma_f32_32x32x16_bf16 v[34:49], v[30:33], v[102:105], v[34:49]
	v_sub_f32_e32 v127, v127, v0
	v_sub_f32_e32 v126, v126, v0
	v_sub_f32_e32 v125, v125, v0
	v_sub_f32_e32 v124, v124, v0
	v_sub_f32_e32 v123, v123, v0
	v_sub_f32_e32 v122, v122, v0
	v_exp_f32_e32 v122, v122
	v_mfma_f32_32x32x16_bf16 v[50:65], v[26:29], v[102:105], v[50:65]
	v_exp_f32_e32 v123, v123
	v_exp_f32_e32 v124, v124
	v_exp_f32_e32 v125, v125
	v_exp_f32_e32 v126, v126
	v_exp_f32_e32 v127, v127
	v_exp_f32_e32 v128, v128
	v_exp_f32_e32 v129, v129
	v_cvt_pk_bf16_f32 v26, v122, v123
	v_cvt_pk_bf16_f32 v27, v124, v125
	v_cvt_pk_bf16_f32 v28, v126, v127
	v_cvt_pk_bf16_f32 v29, v128, v129
	v_sub_f32_e32 v30, v101, v0
	v_sub_f32_e32 v31, v100, v0
	v_mfma_f32_32x32x16_bf16 v[34:49], v[22:25], v[26:29], v[34:49]
	v_sub_f32_e32 v22, v99, v0
	v_sub_f32_e32 v23, v98, v0
	v_exp_f32_e32 v98, v23
	v_exp_f32_e32 v99, v22
	v_exp_f32_e32 v100, v31
	v_exp_f32_e32 v101, v30
	v_exp_f32_e32 v102, v157
	v_mfma_f32_32x32x16_bf16 v[50:65], v[18:21], v[26:29], v[50:65]
	v_exp_f32_e32 v103, v156
	v_exp_f32_e32 v104, v155
	v_exp_f32_e32 v105, v154
	v_cvt_pk_bf16_f32 v18, v98, v99
	v_cvt_pk_bf16_f32 v19, v100, v101
	v_cvt_pk_bf16_f32 v20, v102, v103
	v_cvt_pk_bf16_f32 v21, v104, v105
	v_sub_f32_e32 v113, v113, v0
	v_sub_f32_e32 v112, v112, v0
	v_mfma_f32_32x32x16_bf16 v[34:49], v[14:17], v[18:21], v[34:49]
	v_sub_f32_e32 v111, v111, v0
	v_sub_f32_e32 v110, v110, v0
	v_sub_f32_e32 v109, v109, v0
	v_sub_f32_e32 v108, v108, v0
	v_sub_f32_e32 v14, v107, v0
	v_sub_f32_e32 v0, v106, v0
	v_exp_f32_e32 v106, v0
	v_mfma_f32_32x32x16_bf16 v[50:65], v[10:13], v[18:21], v[50:65]
	v_exp_f32_e32 v107, v14
	v_exp_f32_e32 v108, v108
	v_exp_f32_e32 v109, v109
	v_exp_f32_e32 v110, v110
	v_exp_f32_e32 v111, v111
	v_exp_f32_e32 v112, v112
	v_exp_f32_e32 v113, v113
	v_cvt_pk_bf16_f32 v10, v106, v107
	v_cvt_pk_bf16_f32 v11, v108, v109
	v_cvt_pk_bf16_f32 v12, v110, v111
	v_cvt_pk_bf16_f32 v13, v112, v113
	s_and_b64 vcc, exec, s[0:1]
	s_nop 0
	v_mfma_f32_32x32x16_bf16 v[34:49], v[6:9], v[10:13], v[34:49]
	s_waitcnt lgkmcnt(0)
	v_mfma_f32_32x32x16_bf16 v[50:65], v[2:5], v[10:13], v[50:65]
	s_cbranch_vccnz .LBB0_558
	s_lshl_b32 s4, s26, 6
	s_sub_i32 s0, s49, s4
	s_cmpk_lt_i32 s0, 0x400
	s_mov_b64 s[0:1], -1
	s_cbranch_scc0 .LBB0_555
	v_add_u32_e32 v0, s4, v200
	v_sub_u32_e32 v0, v199, v0
	v_lshl_add_u32 v0, v0, 2, s37
	v_add_u32_e32 v0, 0xd110, v0
	ds_read2_b32 v[2:3], v0 offset0:58 offset1:59
	ds_read2_b32 v[154:155], v0 offset0:26 offset1:27
	ds_read2_b32 v[4:5], v0 offset0:56 offset1:57
	ds_read2_b32 v[20:21], v0 offset0:24 offset1:25
	ds_read2_b32 v[6:7], v0 offset0:50 offset1:51
	ds_read2_b32 v[22:23], v0 offset0:18 offset1:19
	ds_read2_b32 v[8:9], v0 offset0:48 offset1:49
	ds_read2_b32 v[24:25], v0 offset0:16 offset1:17
	ds_read2_b32 v[10:11], v0 offset0:42 offset1:43
	ds_read2_b32 v[26:27], v0 offset0:10 offset1:11
	ds_read2_b32 v[12:13], v0 offset0:40 offset1:41
	ds_read2_b32 v[28:29], v0 offset0:8 offset1:9
	ds_read2_b32 v[14:15], v0 offset0:34 offset1:35
	ds_read2_b32 v[16:17], v0 offset0:32 offset1:33
	ds_read2_b32 v[30:31], v0 offset0:0 offset1:1
	ds_read2_b32 v[32:33], v0 offset0:2 offset1:3
	s_waitcnt lgkmcnt(0)
	v_pk_fma_f32 v[76:77], v[76:77], s[52:53], v[12:13] op_sel:[0,0,1] op_sel_hi:[1,0,0]
	v_pk_fma_f32 v[74:75], v[74:75], s[52:53], v[10:11] op_sel:[0,0,1] op_sel_hi:[1,0,0]
	v_pk_fma_f32 v[78:79], v[78:79], s[52:53], v[14:15] op_sel:[0,0,1] op_sel_hi:[1,0,0]
	v_pk_fma_f32 v[80:81], v[80:81], s[52:53], v[16:17] op_sel:[0,0,1] op_sel_hi:[1,0,0]
	v_pk_fma_f32 v[72:73], v[72:73], s[52:53], v[8:9] op_sel:[0,0,1] op_sel_hi:[1,0,0]
	v_pk_fma_f32 v[70:71], v[70:71], s[52:53], v[6:7] op_sel:[0,0,1] op_sel_hi:[1,0,0]
	v_pk_fma_f32 v[68:69], v[68:69], s[52:53], v[4:5] op_sel:[0,0,1] op_sel_hi:[1,0,0]
	v_pk_fma_f32 v[66:67], v[66:67], s[52:53], v[2:3] op_sel:[0,0,1] op_sel_hi:[1,0,0]
	v_pk_fma_f32 v[96:97], v[96:97], s[52:53], v[30:31] op_sel:[0,0,1] op_sel_hi:[1,0,0]
	v_pk_fma_f32 v[94:95], v[94:95], s[52:53], v[32:33] op_sel:[0,0,1] op_sel_hi:[1,0,0]
	v_pk_fma_f32 v[92:93], v[92:93], s[52:53], v[28:29] op_sel:[0,0,1] op_sel_hi:[1,0,0]
	v_pk_fma_f32 v[90:91], v[90:91], s[52:53], v[26:27] op_sel:[0,0,1] op_sel_hi:[1,0,0]
	v_pk_fma_f32 v[88:89], v[88:89], s[52:53], v[24:25] op_sel:[0,0,1] op_sel_hi:[1,0,0]
	v_pk_fma_f32 v[86:87], v[86:87], s[52:53], v[22:23] op_sel:[0,0,1] op_sel_hi:[1,0,0]
	v_pk_fma_f32 v[84:85], v[84:85], s[52:53], v[20:21] op_sel:[0,0,1] op_sel_hi:[1,0,0]
	v_pk_fma_f32 v[82:83], v[82:83], s[52:53], v[154:155] op_sel:[0,0,1] op_sel_hi:[1,0,0]
	s_mov_b64 s[0:1], 0
	s_branch .LBB0_558
